# v37 + EpiFF epilogue: adjacent scalar f32 mul(-log2e)/add(1.0) pairs merged into v_pk_mul_f32/v_pk_add_f32 where no transcendental-result hazard arises (40 fewer VALU per wave per tile)
# baseline (speedup 1.0000x reference)
; #define PG8_STAGE(bufoff, gbase, voff) do { _Pragma("unroll") for (int _i = 0; _i < 2; ++_i) \
;         __builtin_amdgcn_global_load_lds((const unsigned*)((const char*)(gbase) + (voff)[_i]), (LAS unsigned*)(lds + (bufoff) + ldsw + _i * 8192), 16, 0, 0); } while (0)
; #define PG8_LDA(dst, b, h) do { _Pragma("unroll") for (int m = 0; m < 4; ++m) _Pragma("unroll") for (int k = 0; k < 2; ++k) dst[m][k] = *(const LAS bf16x8*)(lds + PG8_SA(b, h) + aoff + m * 2048 + k * 1024); } while (0)
; #define PG8_LDB(dst, b, h) do { _Pragma("unroll") for (int n = 0; n < 2; ++n) _Pragma("unroll") for (int k = 0; k < 2; ++k) dst[n][k] = *(const LAS bf16x8*)(lds + PG8_SB(b, h) + boff + n * 2048 + k * 1024); } while (0)
; #define PG8_MMA(ai, bj, At, Bt) do { __builtin_amdgcn_s_setprio(1); _Pragma("unroll") for (int m = 0; m < 4; ++m) _Pragma("unroll") for (int n = 0; n < 2; ++n) _Pragma("unroll") for (int k = 0; k < 2; ++k) \
;         acc[ai][bj][m][n] = __builtin_amdgcn_mfma_f32_16x16x32_bf16(Bt[n][k], At[m][k], acc[ai][bj][m][n], 0, 0, 0); __builtin_amdgcn_s_setprio(0); } while (0)
; #define PG8_WAIT_V(n) asm volatile("s_waitcnt vmcnt(" #n ")" ::: "memory")
; #define PG8_WAIT_L(n) asm volatile("s_waitcnt lgkmcnt(" #n ")" ::: "memory")
; #define PG8_BAR __builtin_amdgcn_s_barrier()
; template <class Epi>
; __device__ __forceinline__ void gemm_phase(LAS unsigned char* lds, const Gemm g, const StaticOrder& S, const Epi& E) {
;     ...
;             PG8_LDB(B0, 0, 0); PG8_SCHED; PG8_LDA(At, 0, 0); PG8_STAGE(PG8_SA(1, 1), a1 + hA, voffA);
;             PG8_WAIT_L(8); PG8_BAR; PG8_WAIT_L(0); PG8_MMA(0, 0, At, B0); PG8_BAR; PG8_SCHED;
;             PG8_LDB(B1, 0, 1); PG8_STAGE(PG8_SB(0, 0), b2, voffB);
;             PG8_BAR; PG8_WAIT_L(0); PG8_MMA(0, 1, At, B1); PG8_BAR;
;             PG8_LDA(At, 0, 1); PG8_STAGE(PG8_SA(0, 0), a2, voffA);
;             PG8_BAR; PG8_WAIT_L(0); PG8_MMA(1, 0, At, B0); PG8_BAR; PG8_SCHED;
;             PG8_STAGE(PG8_SB(0, 1), b2 + hB, voffB);
;             PG8_WAIT_V(6); PG8_BAR; PG8_MMA(1, 1, At, B1); PG8_BAR;
;             PG8_LDB(B0, 1, 0); PG8_SCHED; PG8_LDA(At, 1, 0); PG8_STAGE(PG8_SA(0, 1), a2 + hA, voffA);
;             PG8_WAIT_L(8); PG8_BAR; PG8_WAIT_L(0); PG8_MMA(0, 0, At, B0); PG8_BAR; PG8_SCHED;
;             PG8_LDB(B1, 1, 1); PG8_STAGE(PG8_SB(1, 0), b3, voffB);
;             PG8_BAR; PG8_WAIT_L(0); PG8_MMA(0, 1, At, B1); PG8_BAR;
.LBB0_104:
	s_add_u32 s22, s62, 0xfffc0080
	s_addc_u32 s23, s63, -1
	s_add_i32 s75, 0, 0x10000
	s_cmp_eq_u32 s74, 12
	s_cselect_b32 s67, s43, s23
	s_cselect_b32 s66, s61, s22
	s_cselect_b32 s65, s41, s71
	s_cselect_b32 s64, s69, s70
	s_add_i32 m0, s50, 0xc000
	ds_read_b128 v[172:175], v149
	ds_read_b128 v[176:179], v149 offset:1024
	ds_read_b128 v[180:183], v149 offset:2048
	ds_read_b128 v[184:187], v149 offset:3072
	ds_read_b128 v[188:191], v149 offset:4096
	ds_read_b128 v[192:195], v149 offset:5120
	ds_read_b128 v[202:205], v149 offset:6144
	ds_read_b128 v[206:209], v149 offset:7168
	global_load_lds_dwordx4 v138, s[62:63]
	s_add_i32 m0, s50, 0xe000
	s_nop 0
	global_load_lds_dwordx4 v140, s[62:63]
	s_waitcnt lgkmcnt(8)
	s_barrier
	s_waitcnt lgkmcnt(0)
	s_setprio 1
	v_mfma_f32_16x16x32_bf16 v[126:129], v[156:159], v[172:175], v[126:129]
	v_mfma_f32_16x16x32_bf16 v[118:121], v[164:167], v[172:175], v[118:121]
	v_mfma_f32_16x16x32_bf16 v[110:113], v[156:159], v[180:183], v[110:113]
	v_mfma_f32_16x16x32_bf16 v[102:105], v[164:167], v[180:183], v[102:105]
	v_mfma_f32_16x16x32_bf16 v[94:97], v[156:159], v[188:191], v[94:97]
	v_mfma_f32_16x16x32_bf16 v[86:89], v[164:167], v[188:191], v[86:89]
	v_mfma_f32_16x16x32_bf16 v[78:81], v[156:159], v[202:205], v[78:81]
	v_mfma_f32_16x16x32_bf16 v[70:73], v[164:167], v[202:205], v[70:73]
	v_mfma_f32_16x16x32_bf16 v[126:129], v[160:163], v[176:179], v[126:129]
	v_mfma_f32_16x16x32_bf16 v[118:121], v[168:171], v[176:179], v[118:121]
	v_mfma_f32_16x16x32_bf16 v[110:113], v[160:163], v[184:187], v[110:113]
	v_mfma_f32_16x16x32_bf16 v[102:105], v[168:171], v[184:187], v[102:105]
	v_mfma_f32_16x16x32_bf16 v[94:97], v[160:163], v[192:195], v[94:97]
	v_mfma_f32_16x16x32_bf16 v[86:89], v[168:171], v[192:195], v[86:89]
	v_mfma_f32_16x16x32_bf16 v[78:81], v[160:163], v[206:209], v[78:81]
	v_mfma_f32_16x16x32_bf16 v[70:73], v[168:171], v[206:209], v[70:73]
	s_setprio 0
	s_barrier
	s_add_i32 s76, 0, 0x14000
	s_add_i32 s22, s75, s48
	s_mov_b32 m0, s22
	ds_read_b128 v[210:213], v151 offset:16384
	ds_read_b128 v[214:217], v151 offset:17408
	ds_read_b128 v[218:221], v151 offset:18432
	ds_read_b128 v[222:225], v151 offset:19456
	global_load_lds_dwordx4 v0, s[64:65]
	s_add_i32 m0, s22, 0x2000
	s_nop 0
	global_load_lds_dwordx4 v134, s[64:65]
	s_barrier
	s_waitcnt lgkmcnt(0)
	s_setprio 1
	v_mfma_f32_16x16x32_bf16 v[122:125], v[210:213], v[172:175], v[122:125]
	v_mfma_f32_16x16x32_bf16 v[114:117], v[218:221], v[172:175], v[114:117]
	v_mfma_f32_16x16x32_bf16 v[106:109], v[210:213], v[180:183], v[106:109]
	v_mfma_f32_16x16x32_bf16 v[98:101], v[218:221], v[180:183], v[98:101]
	v_mfma_f32_16x16x32_bf16 v[90:93], v[210:213], v[188:191], v[90:93]
	v_mfma_f32_16x16x32_bf16 v[82:85], v[218:221], v[188:191], v[82:85]
	v_mfma_f32_16x16x32_bf16 v[74:77], v[210:213], v[202:205], v[74:77]
	v_mfma_f32_16x16x32_bf16 v[66:69], v[218:221], v[202:205], v[66:69]
	v_mfma_f32_16x16x32_bf16 v[122:125], v[214:217], v[176:179], v[122:125]
	v_mfma_f32_16x16x32_bf16 v[114:117], v[222:225], v[176:179], v[114:117]
	v_mfma_f32_16x16x32_bf16 v[106:109], v[214:217], v[184:187], v[106:109]
	v_mfma_f32_16x16x32_bf16 v[98:101], v[222:225], v[184:187], v[98:101]
	v_mfma_f32_16x16x32_bf16 v[90:93], v[214:217], v[192:195], v[90:93]
	v_mfma_f32_16x16x32_bf16 v[82:85], v[222:225], v[192:195], v[82:85]
	v_mfma_f32_16x16x32_bf16 v[74:77], v[214:217], v[206:209], v[74:77]
	v_mfma_f32_16x16x32_bf16 v[66:69], v[222:225], v[206:209], v[66:69]
	s_setprio 0
	s_mov_b32 m0, s50
	s_barrier
	ds_read_b128 v[172:175], v149 offset:16384
	ds_read_b128 v[176:179], v149 offset:17408
	ds_read_b128 v[180:183], v149 offset:18432
	ds_read_b128 v[184:187], v149 offset:19456
	ds_read_b128 v[188:191], v149 offset:20480
	ds_read_b128 v[192:195], v149 offset:21504
	ds_read_b128 v[202:205], v149 offset:22528
	ds_read_b128 v[206:209], v149 offset:23552
	global_load_lds_dwordx4 v130, s[66:67]
	s_mov_b32 m0, s51
	s_nop 0
	global_load_lds_dwordx4 v132, s[66:67]
	s_waitcnt vmcnt(8)
	s_barrier
	s_waitcnt lgkmcnt(0)
	s_setprio 1
	v_mfma_f32_16x16x32_bf16 v[62:65], v[156:159], v[172:175], v[62:65]
	v_mfma_f32_16x16x32_bf16 v[54:57], v[164:167], v[172:175], v[54:57]
	v_mfma_f32_16x16x32_bf16 v[46:49], v[156:159], v[180:183], v[46:49]
	v_mfma_f32_16x16x32_bf16 v[38:41], v[164:167], v[180:183], v[38:41]
	v_mfma_f32_16x16x32_bf16 v[30:33], v[156:159], v[188:191], v[30:33]
	v_mfma_f32_16x16x32_bf16 v[22:25], v[164:167], v[188:191], v[22:25]
	v_mfma_f32_16x16x32_bf16 v[14:17], v[156:159], v[202:205], v[14:17]
	v_mfma_f32_16x16x32_bf16 v[6:9], v[164:167], v[202:205], v[6:9]
	v_mfma_f32_16x16x32_bf16 v[62:65], v[160:163], v[176:179], v[62:65]
	v_mfma_f32_16x16x32_bf16 v[54:57], v[168:171], v[176:179], v[54:57]
	v_mfma_f32_16x16x32_bf16 v[46:49], v[160:163], v[184:187], v[46:49]
	v_mfma_f32_16x16x32_bf16 v[38:41], v[168:171], v[184:187], v[38:41]
	v_mfma_f32_16x16x32_bf16 v[30:33], v[160:163], v[192:195], v[30:33]
	v_mfma_f32_16x16x32_bf16 v[22:25], v[168:171], v[192:195], v[22:25]
	v_mfma_f32_16x16x32_bf16 v[14:17], v[160:163], v[206:209], v[14:17]
	v_mfma_f32_16x16x32_bf16 v[6:9], v[168:171], v[206:209], v[6:9]
	s_setprio 0
	s_barrier
	s_add_u32 s22, s64, 0x40000
	s_addc_u32 s23, s65, 0
	s_add_i32 s75, s76, s48
	s_mov_b32 m0, s75
	s_nop 0
	global_load_lds_dwordx4 v0, s[22:23]
	s_add_i32 m0, s75, 0x2000
	s_nop 0
	global_load_lds_dwordx4 v134, s[22:23]
	s_waitcnt vmcnt(6)
	s_barrier
; #define PG8_STAGE(bufoff, gbase, voff) do { _Pragma("unroll") for (int _i = 0; _i < 2; ++_i) \
;         __builtin_amdgcn_global_load_lds((const unsigned*)((const char*)(gbase) + (voff)[_i]), (LAS unsigned*)(lds + (bufoff) + ldsw + _i * 8192), 16, 0, 0); } while (0)
; #define PG8_LDA(dst, b, h) do { _Pragma("unroll") for (int m = 0; m < 4; ++m) _Pragma("unroll") for (int k = 0; k < 2; ++k) dst[m][k] = *(const LAS bf16x8*)(lds + PG8_SA(b, h) + aoff + m * 2048 + k * 1024); } while (0)
; #define PG8_LDB(dst, b, h) do { _Pragma("unroll") for (int n = 0; n < 2; ++n) _Pragma("unroll") for (int k = 0; k < 2; ++k) dst[n][k] = *(const LAS bf16x8*)(lds + PG8_SB(b, h) + boff + n * 2048 + k * 1024); } while (0)
; #define PG8_MMA(ai, bj, At, Bt) do { __builtin_amdgcn_s_setprio(1); _Pragma("unroll") for (int m = 0; m < 4; ++m) _Pragma("unroll") for (int n = 0; n < 2; ++n) _Pragma("unroll") for (int k = 0; k < 2; ++k) \
;         acc[ai][bj][m][n] = __builtin_amdgcn_mfma_f32_16x16x32_bf16(Bt[n][k], At[m][k], acc[ai][bj][m][n], 0, 0, 0); __builtin_amdgcn_s_setprio(0); } while (0)
; #define PG8_WAIT_L(n) asm volatile("s_waitcnt lgkmcnt(" #n ")" ::: "memory")
; #define PG8_BAR __builtin_amdgcn_s_barrier()
; #define PG8_SCHED __builtin_amdgcn_sched_barrier(0)
; template <class Epi>
; __device__ __forceinline__ void gemm_phase(LAS unsigned char* lds, const Gemm g, const StaticOrder& S, const Epi& E) {
;     ...
;             PG8_LDB(B0, 1, 0); PG8_SCHED; PG8_LDA(At, 1, 0); PG8_STAGE(PG8_SA(0, 1), a2 + hA, voffA);
;             PG8_WAIT_L(8); PG8_BAR; PG8_WAIT_L(0); PG8_MMA(0, 0, At, B0); PG8_BAR; PG8_SCHED;
;             PG8_LDB(B1, 1, 1); PG8_STAGE(PG8_SB(1, 0), b3, voffB);
;             PG8_BAR; PG8_WAIT_L(0); PG8_MMA(0, 1, At, B1); PG8_BAR;
;             PG8_LDA(At, 1, 1); PG8_STAGE(PG8_SA(1, 0), a3, voffA);
;             PG8_BAR; PG8_WAIT_L(0); PG8_MMA(1, 0, At, B0); PG8_BAR; PG8_SCHED;
	s_setprio 1
	v_mfma_f32_16x16x32_bf16 v[58:61], v[210:213], v[172:175], v[58:61]
	ds_read_b128 v[156:159], v151 offset:32768
	v_mfma_f32_16x16x32_bf16 v[50:53], v[218:221], v[172:175], v[50:53]
	ds_read_b128 v[160:163], v151 offset:33792
	v_mfma_f32_16x16x32_bf16 v[42:45], v[210:213], v[180:183], v[42:45]
	ds_read_b128 v[164:167], v151 offset:34816
	v_mfma_f32_16x16x32_bf16 v[34:37], v[218:221], v[180:183], v[34:37]
	ds_read_b128 v[168:171], v151 offset:35840
	v_mfma_f32_16x16x32_bf16 v[26:29], v[210:213], v[188:191], v[26:29]
	v_mfma_f32_16x16x32_bf16 v[18:21], v[218:221], v[188:191], v[18:21]
	v_mfma_f32_16x16x32_bf16 v[10:13], v[210:213], v[202:205], v[10:13]
	v_mfma_f32_16x16x32_bf16 v[2:5], v[218:221], v[202:205], v[2:5]
	v_mfma_f32_16x16x32_bf16 v[58:61], v[214:217], v[176:179], v[58:61]
	v_mfma_f32_16x16x32_bf16 v[50:53], v[222:225], v[176:179], v[50:53]
	v_mfma_f32_16x16x32_bf16 v[42:45], v[214:217], v[184:187], v[42:45]
	v_mfma_f32_16x16x32_bf16 v[34:37], v[222:225], v[184:187], v[34:37]
	v_mfma_f32_16x16x32_bf16 v[26:29], v[214:217], v[192:195], v[26:29]
	v_mfma_f32_16x16x32_bf16 v[18:21], v[222:225], v[192:195], v[18:21]
	v_mfma_f32_16x16x32_bf16 v[10:13], v[214:217], v[206:209], v[10:13]
	v_mfma_f32_16x16x32_bf16 v[2:5], v[222:225], v[206:209], v[2:5]
	s_setprio 0
	s_add_i32 s75, 0, 0x18000
	s_barrier
	s_add_u32 s22, s66, 0x40000
	s_addc_u32 s23, s67, 0
	s_mov_b32 m0, s53
	ds_read_b128 v[172:175], v149 offset:32768
	ds_read_b128 v[176:179], v149 offset:33792
	ds_read_b128 v[180:183], v149 offset:34816
	ds_read_b128 v[184:187], v149 offset:35840
	ds_read_b128 v[188:191], v149 offset:36864
	ds_read_b128 v[192:195], v149 offset:37888
	ds_read_b128 v[202:205], v149 offset:38912
	ds_read_b128 v[206:209], v149 offset:39936
	global_load_lds_dwordx4 v130, s[22:23]
	s_mov_b32 m0, s54
	s_nop 0
	global_load_lds_dwordx4 v132, s[22:23]
	s_waitcnt lgkmcnt(8)
	s_barrier
	s_waitcnt lgkmcnt(0)
	s_setprio 1
	v_mfma_f32_16x16x32_bf16 v[126:129], v[156:159], v[172:175], v[126:129]
	v_mfma_f32_16x16x32_bf16 v[118:121], v[164:167], v[172:175], v[118:121]
	v_mfma_f32_16x16x32_bf16 v[110:113], v[156:159], v[180:183], v[110:113]
	v_mfma_f32_16x16x32_bf16 v[102:105], v[164:167], v[180:183], v[102:105]
	v_mfma_f32_16x16x32_bf16 v[94:97], v[156:159], v[188:191], v[94:97]
	v_mfma_f32_16x16x32_bf16 v[86:89], v[164:167], v[188:191], v[86:89]
	v_mfma_f32_16x16x32_bf16 v[78:81], v[156:159], v[202:205], v[78:81]
	v_mfma_f32_16x16x32_bf16 v[70:73], v[164:167], v[202:205], v[70:73]
	v_mfma_f32_16x16x32_bf16 v[126:129], v[160:163], v[176:179], v[126:129]
	v_mfma_f32_16x16x32_bf16 v[118:121], v[168:171], v[176:179], v[118:121]
	v_mfma_f32_16x16x32_bf16 v[110:113], v[160:163], v[184:187], v[110:113]
	v_mfma_f32_16x16x32_bf16 v[102:105], v[168:171], v[184:187], v[102:105]
	v_mfma_f32_16x16x32_bf16 v[94:97], v[160:163], v[192:195], v[94:97]
	v_mfma_f32_16x16x32_bf16 v[86:89], v[168:171], v[192:195], v[86:89]
	v_mfma_f32_16x16x32_bf16 v[78:81], v[160:163], v[206:209], v[78:81]
	v_mfma_f32_16x16x32_bf16 v[70:73], v[168:171], v[206:209], v[70:73]
	s_setprio 0
	s_barrier
	s_add_i32 s22, s75, s48
	s_add_u32 s100, s64, 0x80
	s_addc_u32 s101, s65, 0
	s_mov_b32 m0, s22
	ds_read_b128 v[210:213], v151 offset:49152
	ds_read_b128 v[214:217], v151 offset:50176
	ds_read_b128 v[218:221], v151 offset:51200
	ds_read_b128 v[222:225], v151 offset:52224
	global_load_lds_dwordx4 v0, s[100:101]
	s_add_i32 m0, s22, 0x2000
	s_nop 0
	global_load_lds_dwordx4 v134, s[100:101]
	s_barrier
	s_waitcnt lgkmcnt(0)
	s_setprio 1
	v_mfma_f32_16x16x32_bf16 v[122:125], v[210:213], v[172:175], v[122:125]
	v_mfma_f32_16x16x32_bf16 v[114:117], v[218:221], v[172:175], v[114:117]
	v_mfma_f32_16x16x32_bf16 v[106:109], v[210:213], v[180:183], v[106:109]
	v_mfma_f32_16x16x32_bf16 v[98:101], v[218:221], v[180:183], v[98:101]
	v_mfma_f32_16x16x32_bf16 v[90:93], v[210:213], v[188:191], v[90:93]
	v_mfma_f32_16x16x32_bf16 v[82:85], v[218:221], v[188:191], v[82:85]
	v_mfma_f32_16x16x32_bf16 v[74:77], v[210:213], v[202:205], v[74:77]
	v_mfma_f32_16x16x32_bf16 v[66:69], v[218:221], v[202:205], v[66:69]
	v_mfma_f32_16x16x32_bf16 v[122:125], v[214:217], v[176:179], v[122:125]
	v_mfma_f32_16x16x32_bf16 v[114:117], v[222:225], v[176:179], v[114:117]
	v_mfma_f32_16x16x32_bf16 v[106:109], v[214:217], v[184:187], v[106:109]
	v_mfma_f32_16x16x32_bf16 v[98:101], v[222:225], v[184:187], v[98:101]
	v_mfma_f32_16x16x32_bf16 v[90:93], v[214:217], v[192:195], v[90:93]
	v_mfma_f32_16x16x32_bf16 v[82:85], v[222:225], v[192:195], v[82:85]
	v_mfma_f32_16x16x32_bf16 v[74:77], v[214:217], v[206:209], v[74:77]
	v_mfma_f32_16x16x32_bf16 v[66:69], v[222:225], v[206:209], v[66:69]
	s_setprio 0
	s_mov_b32 m0, s56
	s_add_u32 s100, s66, 0x80
	s_addc_u32 s101, s67, 0
	s_barrier
	ds_read_b128 v[172:175], v149 offset:49152
	ds_read_b128 v[176:179], v149 offset:50176
	ds_read_b128 v[180:183], v149 offset:51200
	ds_read_b128 v[184:187], v149 offset:52224
	ds_read_b128 v[188:191], v149 offset:53248
	ds_read_b128 v[192:195], v149 offset:54272
	ds_read_b128 v[202:205], v149 offset:55296
	ds_read_b128 v[206:209], v149 offset:56320
	global_load_lds_dwordx4 v130, s[100:101]
	s_mov_b32 m0, s57
	s_nop 0
	global_load_lds_dwordx4 v132, s[100:101]
	s_waitcnt vmcnt(8)
	s_barrier
; __device__ __forceinline__ float siluf_(float x) { return x * sigmoidf_(x); }
; #define PG8_STAGE(bufoff, gbase, voff) do { _Pragma("unroll") for (int _i = 0; _i < 2; ++_i) \
;         __builtin_amdgcn_global_load_lds((const unsigned*)((const char*)(gbase) + (voff)[_i]), (LAS unsigned*)(lds + (bufoff) + ldsw + _i * 8192), 16, 0, 0); } while (0)
; #define PG8_MMA(ai, bj, At, Bt) do { __builtin_amdgcn_s_setprio(1); _Pragma("unroll") for (int m = 0; m < 4; ++m) _Pragma("unroll") for (int n = 0; n < 2; ++n) _Pragma("unroll") for (int k = 0; k < 2; ++k) \
;         acc[ai][bj][m][n] = __builtin_amdgcn_mfma_f32_16x16x32_bf16(Bt[n][k], At[m][k], acc[ai][bj][m][n], 0, 0, 0); __builtin_amdgcn_s_setprio(0); } while (0)
; #define PG8_WAIT_V(n) asm volatile("s_waitcnt vmcnt(" #n ")" ::: "memory")
; #define PG8_WAIT_L(n) asm volatile("s_waitcnt lgkmcnt(" #n ")" ::: "memory")
; #define PG8_BAR __builtin_amdgcn_s_barrier()
; #define PG8_SCHED __builtin_amdgcn_sched_barrier(0)
; __device__ __forceinline__ u32x4 pack8(const f32x4 a, const f32x4 b) { u32x4 w; w.x = cvt_pk_bf16(a[0], a[1]); w.y = cvt_pk_bf16(a[2], a[3]); w.z = cvt_pk_bf16(b[0], b[1]); w.w = cvt_pk_bf16(b[2], b[3]); return w; }
; template <class Epi>
; __device__ __forceinline__ void gemm_phase(LAS unsigned char* lds, const Gemm g, const StaticOrder& S, const Epi& E) {
;     ...
;             PG8_BAR; PG8_WAIT_L(0); PG8_MMA(1, 0, At, B0); PG8_BAR; PG8_SCHED;
;             PG8_STAGE(PG8_SB(1, 1), b3 + hB, voffB);
;             PG8_WAIT_V(6); PG8_BAR; PG8_MMA(1, 1, At, B1); PG8_BAR;
;         }
;     __device__ __forceinline__ void operator()(const Acc& acc, const Unit& u, int wr, int wc, int fr, int fq, const RsPre& pr) const {
;         asm volatile("" : "+v"(fr), "+v"(fq));
;         const int row0 = u.pm * 256 + wr * 64 + fr, col0 = u.pn * 128 + wc * 32 + 8 * fq;
;         const float (&rs)[2][4] = pr.rs;
; #pragma unroll
;         for (int ai = 0; ai < 2; ++ai)
; #pragma unroll
;             for (int m = 0; m < 4; ++m) { f32x4 o[2];
; #pragma unroll
;                 for (int n = 0; n < 2; ++n) { const f32x4 a1 = acc[ai][0][m][n] * rs[ai][m], a3 = acc[ai][1][m][n] * rs[ai][m];
;                     o[n] = (f32x4){siluf_(a1[0]) * a3[0], siluf_(a1[1]) * a3[1], siluf_(a1[2]) * a3[2], siluf_(a1[3]) * a3[3]}; }
;                 *(u32x4*)(ff + (size_t)(row0 + ai * 128 + m * 16) * DFF + col0) = pack8(o[0], o[1]); }
	s_waitcnt lgkmcnt(0)
	s_setprio 1
	v_mfma_f32_16x16x32_bf16 v[62:65], v[156:159], v[172:175], v[62:65]
	v_mfma_f32_16x16x32_bf16 v[54:57], v[164:167], v[172:175], v[54:57]
	v_mfma_f32_16x16x32_bf16 v[46:49], v[156:159], v[180:183], v[46:49]
	v_mfma_f32_16x16x32_bf16 v[38:41], v[164:167], v[180:183], v[38:41]
	v_mfma_f32_16x16x32_bf16 v[30:33], v[156:159], v[188:191], v[30:33]
	v_mfma_f32_16x16x32_bf16 v[22:25], v[164:167], v[188:191], v[22:25]
	v_mfma_f32_16x16x32_bf16 v[14:17], v[156:159], v[202:205], v[14:17]
	v_mfma_f32_16x16x32_bf16 v[6:9], v[164:167], v[202:205], v[6:9]
	v_mfma_f32_16x16x32_bf16 v[62:65], v[160:163], v[176:179], v[62:65]
	v_mfma_f32_16x16x32_bf16 v[54:57], v[168:171], v[176:179], v[54:57]
	v_mfma_f32_16x16x32_bf16 v[46:49], v[160:163], v[184:187], v[46:49]
	v_mfma_f32_16x16x32_bf16 v[38:41], v[168:171], v[184:187], v[38:41]
	v_mfma_f32_16x16x32_bf16 v[30:33], v[160:163], v[192:195], v[30:33]
	v_mfma_f32_16x16x32_bf16 v[22:25], v[168:171], v[192:195], v[22:25]
	v_mfma_f32_16x16x32_bf16 v[14:17], v[160:163], v[206:209], v[14:17]
	v_mfma_f32_16x16x32_bf16 v[6:9], v[168:171], v[206:209], v[6:9]
	s_setprio 0
	s_barrier
	s_add_u32 s22, s64, 0x40080
	s_addc_u32 s23, s65, 0
	s_add_i32 s64, s48, 0x1c000
	s_mov_b32 m0, s64
	s_nop 0
	global_load_lds_dwordx4 v0, s[22:23]
	s_add_i32 m0, s64, 0x2000
	s_nop 0
	global_load_lds_dwordx4 v134, s[22:23]
	s_waitcnt vmcnt(6)
	s_barrier
	s_setprio 1
	v_mfma_f32_16x16x32_bf16 v[58:61], v[210:213], v[172:175], v[58:61]
	ds_read_b128 v[156:159], v151
	v_mfma_f32_16x16x32_bf16 v[50:53], v[218:221], v[172:175], v[50:53]
	ds_read_b128 v[160:163], v151 offset:1024
	v_mfma_f32_16x16x32_bf16 v[42:45], v[210:213], v[180:183], v[42:45]
	ds_read_b128 v[164:167], v151 offset:2048
	v_mfma_f32_16x16x32_bf16 v[34:37], v[218:221], v[180:183], v[34:37]
	ds_read_b128 v[168:171], v151 offset:3072
	v_mfma_f32_16x16x32_bf16 v[26:29], v[210:213], v[188:191], v[26:29]
	v_mfma_f32_16x16x32_bf16 v[18:21], v[218:221], v[188:191], v[18:21]
	v_mfma_f32_16x16x32_bf16 v[10:13], v[210:213], v[202:205], v[10:13]
	v_mfma_f32_16x16x32_bf16 v[2:5], v[218:221], v[202:205], v[2:5]
	v_mfma_f32_16x16x32_bf16 v[58:61], v[214:217], v[176:179], v[58:61]
	v_mfma_f32_16x16x32_bf16 v[50:53], v[222:225], v[176:179], v[50:53]
	v_mfma_f32_16x16x32_bf16 v[42:45], v[214:217], v[184:187], v[42:45]
	v_mfma_f32_16x16x32_bf16 v[34:37], v[222:225], v[184:187], v[34:37]
	v_mfma_f32_16x16x32_bf16 v[26:29], v[214:217], v[192:195], v[26:29]
	v_mfma_f32_16x16x32_bf16 v[18:21], v[222:225], v[192:195], v[18:21]
	v_mfma_f32_16x16x32_bf16 v[10:13], v[214:217], v[206:209], v[10:13]
	v_mfma_f32_16x16x32_bf16 v[2:5], v[222:225], v[206:209], v[2:5]
	s_setprio 0
	s_add_i32 s74, s74, 2
	s_add_u32 s62, s62, 0x100
	s_addc_u32 s63, s63, 0
	s_add_u32 s70, s70, 0x100
	s_addc_u32 s71, s71, 0
	s_cmp_gt_u32 s74, 13
	s_barrier
	s_cbranch_scc0 .LBB0_104
	s_mov_b32 s100, 0xbfb8aa3b
	s_mov_b32 s101, 0xbfb8aa3b
	s_waitcnt lgkmcnt(0)
	v_mov_b32_e32 v151, v137
	v_mov_b32_e32 v153, v143
	s_lshl_b32 s22, s60, 8
	s_add_i32 s22, s22, s49
	v_add_u32_e32 v151, s22, v151
	s_lshl_b32 s22, s33, 7
	s_or_b32 s22, s22, s55
	s_waitcnt vmcnt(0)
	v_pk_mul_f32 v[126:127], v[154:155], v[126:127] op_sel_hi:[0,1]
	v_lshl_add_u32 v156, v153, 3, s22
	v_mul_f32_e32 v153, 0xbfb8aa3b, v126
	v_exp_f32_e32 v153, v153
	v_pk_mul_f32 v[128:129], v[154:155], v[128:129] op_sel_hi:[0,1]
	v_pk_mul_f32 v[122:123], v[154:155], v[122:123] op_sel_hi:[0,1]
	v_pk_mul_f32 v[124:125], v[154:155], v[124:125] op_sel_hi:[0,1]
	v_add_f32_e32 v153, 1.0, v153
	v_rcp_f32_e32 v158, v153
	v_mul_f32_e32 v153, 0xbfb8aa3b, v127
	v_exp_f32_e32 v153, v153
	v_pk_mul_f32 v[118:119], v[154:155], v[118:119] op_sel_hi:[0,1]
	v_pk_mul_f32 v[120:121], v[154:155], v[120:121] op_sel_hi:[0,1]
	v_pk_mul_f32 v[114:115], v[154:155], v[114:115] op_sel_hi:[0,1]
	v_add_f32_e32 v153, 1.0, v153
	v_rcp_f32_e32 v159, v153
	v_pk_mul_f32 v[116:117], v[154:155], v[116:117] op_sel_hi:[0,1]
	s_movk_i32 s0, 0x1600
	v_pk_mul_f32 v[126:127], v[126:127], v[158:159]
	v_pk_mul_f32 v[110:111], v[152:153], v[110:111] op_sel_hi:[0,1]
	v_pk_mul_f32 v[122:123], v[126:127], v[122:123]
	v_pk_mul_f32 v[126:127], v[128:129], s[100:101]
	v_exp_f32_e32 v126, v126
	v_exp_f32_e32 v127, v127
	v_pk_mul_f32 v[112:113], v[152:153], v[112:113] op_sel_hi:[0,1]
	v_pk_mul_f32 v[106:107], v[152:153], v[106:107] op_sel_hi:[0,1]
	v_pk_add_f32 v[126:127], v[126:127], 1.0 op_sel_hi:[1,0]
	v_rcp_f32_e32 v126, v126
	v_rcp_f32_e32 v127, v127
	v_pk_mul_f32 v[108:109], v[152:153], v[108:109] op_sel_hi:[0,1]
	v_pk_mul_f32 v[102:103], v[152:153], v[102:103] op_sel_hi:[0,1]
	v_pk_mul_f32 v[104:105], v[152:153], v[104:105] op_sel_hi:[0,1]
	v_pk_mul_f32 v[126:127], v[128:129], v[126:127]
	v_pk_mul_f32 v[98:99], v[152:153], v[98:99] op_sel_hi:[0,1]
	v_pk_mul_f32 v[124:125], v[126:127], v[124:125]
	v_pk_mul_f32 v[126:127], v[118:119], s[100:101]
	v_exp_f32_e32 v126, v126
	v_exp_f32_e32 v127, v127
	v_pk_mul_f32 v[100:101], v[152:153], v[100:101] op_sel_hi:[0,1]
	v_pk_mul_f32 v[94:95], v[150:151], v[94:95] op_sel_hi:[0,1]
	v_pk_add_f32 v[126:127], v[126:127], 1.0 op_sel_hi:[1,0]
	v_rcp_f32_e32 v126, v126
	v_rcp_f32_e32 v127, v127
	v_pk_mul_f32 v[96:97], v[150:151], v[96:97] op_sel_hi:[0,1]
	v_pk_mul_f32 v[90:91], v[150:151], v[90:91] op_sel_hi:[0,1]
	v_pk_mul_f32 v[92:93], v[150:151], v[92:93] op_sel_hi:[0,1]
	v_pk_mul_f32 v[118:119], v[118:119], v[126:127]
	v_pk_mul_f32 v[86:87], v[150:151], v[86:87] op_sel_hi:[0,1]
	v_pk_mul_f32 v[114:115], v[118:119], v[114:115]
	v_pk_mul_f32 v[118:119], v[120:121], s[100:101]
	v_exp_f32_e32 v118, v118
	v_exp_f32_e32 v119, v119
; __device__ __forceinline__ float siluf_(float x) { return x * sigmoidf_(x); }
; __device__ __forceinline__ u32x4 pack8(const f32x4 a, const f32x4 b) { u32x4 w; w.x = cvt_pk_bf16(a[0], a[1]); w.y = cvt_pk_bf16(a[2], a[3]); w.z = cvt_pk_bf16(b[0], b[1]); w.w = cvt_pk_bf16(b[2], b[3]); return w; }
;     __device__ __forceinline__ void operator()(const Acc& acc, const Unit& u, int wr, int wc, int fr, int fq, const RsPre& pr) const {
;     ...
;             for (int m = 0; m < 4; ++m) { f32x4 o[2];
; #pragma unroll
;                 for (int n = 0; n < 2; ++n) { const f32x4 a1 = acc[ai][0][m][n] * rs[ai][m], a3 = acc[ai][1][m][n] * rs[ai][m];
;                     o[n] = (f32x4){siluf_(a1[0]) * a3[0], siluf_(a1[1]) * a3[1], siluf_(a1[2]) * a3[2], siluf_(a1[3]) * a3[3]}; }
;                 *(u32x4*)(ff + (size_t)(row0 + ai * 128 + m * 16) * DFF + col0) = pack8(o[0], o[1]); }
	v_pk_mul_f32 v[88:89], v[150:151], v[88:89] op_sel_hi:[0,1]
	v_pk_mul_f32 v[82:83], v[150:151], v[82:83] op_sel_hi:[0,1]
	v_pk_add_f32 v[118:119], v[118:119], 1.0 op_sel_hi:[1,0]
	v_rcp_f32_e32 v118, v118
	v_rcp_f32_e32 v119, v119
	v_pk_mul_f32 v[84:85], v[150:151], v[84:85] op_sel_hi:[0,1]
	v_pk_mul_f32 v[78:79], v[148:149], v[78:79] op_sel_hi:[0,1]
	v_pk_mul_f32 v[80:81], v[148:149], v[80:81] op_sel_hi:[0,1]
	v_pk_mul_f32 v[118:119], v[120:121], v[118:119]
	v_cvt_pk_bf16_f32 v120, v114, v115
	v_pk_mul_f32 v[116:117], v[118:119], v[116:117]
	v_cvt_pk_bf16_f32 v118, v122, v123
	v_cvt_pk_bf16_f32 v121, v116, v117
	v_lshlrev_b32_e32 v116, 1, v156
	v_mad_u32_u24 v114, v151, s0, v116
	v_cvt_pk_bf16_f32 v119, v124, v125
	global_store_dwordx4 v114, v[118:121], s[20:21]
	v_pk_mul_f32 v[74:75], v[148:149], v[74:75] op_sel_hi:[0,1]
	v_pk_mul_f32 v[76:77], v[148:149], v[76:77] op_sel_hi:[0,1]
	v_pk_mul_f32 v[118:119], v[110:111], s[100:101]
	v_exp_f32_e32 v118, v118
	v_exp_f32_e32 v119, v119
	v_pk_mul_f32 v[70:71], v[148:149], v[70:71] op_sel_hi:[0,1]
	v_pk_mul_f32 v[72:73], v[148:149], v[72:73] op_sel_hi:[0,1]
	v_pk_add_f32 v[118:119], v[118:119], 1.0 op_sel_hi:[1,0]
	v_rcp_f32_e32 v118, v118
	v_rcp_f32_e32 v119, v119
	v_pk_mul_f32 v[66:67], v[148:149], v[66:67] op_sel_hi:[0,1]
	v_pk_mul_f32 v[68:69], v[148:149], v[68:69] op_sel_hi:[0,1]
	v_pk_mul_f32 v[62:63], v[146:147], v[62:63] op_sel_hi:[0,1]
	v_pk_mul_f32 v[110:111], v[110:111], v[118:119]
	v_pk_mul_f32 v[64:65], v[146:147], v[64:65] op_sel_hi:[0,1]
	v_pk_mul_f32 v[106:107], v[110:111], v[106:107]
	v_pk_mul_f32 v[110:111], v[112:113], s[100:101]
	v_exp_f32_e32 v110, v110
	v_exp_f32_e32 v111, v111
	v_pk_mul_f32 v[58:59], v[146:147], v[58:59] op_sel_hi:[0,1]
	v_pk_mul_f32 v[60:61], v[146:147], v[60:61] op_sel_hi:[0,1]
	v_pk_add_f32 v[110:111], v[110:111], 1.0 op_sel_hi:[1,0]
	v_rcp_f32_e32 v110, v110
	v_rcp_f32_e32 v111, v111
	v_pk_mul_f32 v[54:55], v[146:147], v[54:55] op_sel_hi:[0,1]
	v_pk_mul_f32 v[56:57], v[146:147], v[56:57] op_sel_hi:[0,1]
	v_pk_mul_f32 v[50:51], v[146:147], v[50:51] op_sel_hi:[0,1]
	v_pk_mul_f32 v[110:111], v[112:113], v[110:111]
	v_pk_mul_f32 v[52:53], v[146:147], v[52:53] op_sel_hi:[0,1]
	v_pk_mul_f32 v[108:109], v[110:111], v[108:109]
	v_pk_mul_f32 v[110:111], v[102:103], s[100:101]
	v_exp_f32_e32 v110, v110
	v_exp_f32_e32 v111, v111
	v_pk_mul_f32 v[46:47], v[144:145], v[46:47] op_sel_hi:[0,1]
	v_pk_mul_f32 v[48:49], v[144:145], v[48:49] op_sel_hi:[0,1]
	v_pk_add_f32 v[110:111], v[110:111], 1.0 op_sel_hi:[1,0]
	v_rcp_f32_e32 v110, v110
	v_rcp_f32_e32 v111, v111
	v_pk_mul_f32 v[42:43], v[144:145], v[42:43] op_sel_hi:[0,1]
	v_pk_mul_f32 v[44:45], v[144:145], v[44:45] op_sel_hi:[0,1]
	v_pk_mul_f32 v[38:39], v[144:145], v[38:39] op_sel_hi:[0,1]
	v_pk_mul_f32 v[102:103], v[102:103], v[110:111]
	v_pk_mul_f32 v[40:41], v[144:145], v[40:41] op_sel_hi:[0,1]
	v_pk_mul_f32 v[102:103], v[102:103], v[98:99]
	v_pk_mul_f32 v[98:99], v[104:105], s[100:101]
	v_exp_f32_e32 v98, v98
	v_exp_f32_e32 v99, v99
	v_pk_mul_f32 v[34:35], v[144:145], v[34:35] op_sel_hi:[0,1]
	v_pk_mul_f32 v[36:37], v[144:145], v[36:37] op_sel_hi:[0,1]
	v_pk_add_f32 v[98:99], v[98:99], 1.0 op_sel_hi:[1,0]
	v_rcp_f32_e32 v98, v98
	v_rcp_f32_e32 v99, v99
	v_pk_mul_f32 v[30:31], v[142:143], v[30:31] op_sel_hi:[0,1]
	v_pk_mul_f32 v[32:33], v[142:143], v[32:33] op_sel_hi:[0,1]
	v_pk_mul_f32 v[26:27], v[142:143], v[26:27] op_sel_hi:[0,1]
	v_pk_mul_f32 v[98:99], v[104:105], v[98:99]
	v_pk_mul_f32 v[28:29], v[142:143], v[28:29] op_sel_hi:[0,1]
	v_pk_mul_f32 v[104:105], v[98:99], v[100:101]
	v_cvt_pk_bf16_f32 v100, v102, v103
	v_cvt_pk_bf16_f32 v98, v106, v107
	v_cvt_pk_bf16_f32 v99, v108, v109
	v_cvt_pk_bf16_f32 v101, v104, v105
	v_add_u32_e32 v102, 0x16000, v114
	global_store_dwordx4 v102, v[98:101], s[20:21]
	v_pk_mul_f32 v[22:23], v[142:143], v[22:23] op_sel_hi:[0,1]
	v_pk_mul_f32 v[24:25], v[142:143], v[24:25] op_sel_hi:[0,1]
	v_pk_mul_f32 v[98:99], v[94:95], s[100:101]
	v_exp_f32_e32 v98, v98
	v_exp_f32_e32 v99, v99
	v_pk_mul_f32 v[18:19], v[142:143], v[18:19] op_sel_hi:[0,1]
	v_pk_mul_f32 v[20:21], v[142:143], v[20:21] op_sel_hi:[0,1]
	v_pk_add_f32 v[98:99], v[98:99], 1.0 op_sel_hi:[1,0]
	v_rcp_f32_e32 v98, v98
	v_rcp_f32_e32 v99, v99
	v_pk_mul_f32 v[14:15], v[136:137], v[14:15] op_sel_hi:[0,1]
	v_pk_mul_f32 v[16:17], v[136:137], v[16:17] op_sel_hi:[0,1]
	v_pk_mul_f32 v[10:11], v[136:137], v[10:11] op_sel_hi:[0,1]
	v_pk_mul_f32 v[94:95], v[94:95], v[98:99]
	v_pk_mul_f32 v[12:13], v[136:137], v[12:13] op_sel_hi:[0,1]
	v_pk_mul_f32 v[90:91], v[94:95], v[90:91]
	v_pk_mul_f32 v[94:95], v[96:97], s[100:101]
	v_exp_f32_e32 v94, v94
	v_exp_f32_e32 v95, v95
	v_pk_mul_f32 v[6:7], v[136:137], v[6:7] op_sel_hi:[0,1]
	v_pk_mul_f32 v[8:9], v[136:137], v[8:9] op_sel_hi:[0,1]
	v_pk_add_f32 v[94:95], v[94:95], 1.0 op_sel_hi:[1,0]
	v_rcp_f32_e32 v94, v94
	v_rcp_f32_e32 v95, v95
	v_pk_mul_f32 v[2:3], v[136:137], v[2:3] op_sel_hi:[0,1]
	v_pk_mul_f32 v[4:5], v[136:137], v[4:5] op_sel_hi:[0,1]
	s_mov_b64 s[60:61], -1
	v_pk_mul_f32 v[94:95], v[96:97], v[94:95]
	s_and_b64 vcc, vcc, exec
	v_pk_mul_f32 v[92:93], v[94:95], v[92:93]
	v_pk_mul_f32 v[94:95], v[86:87], s[100:101]
	v_exp_f32_e32 v94, v94
	v_exp_f32_e32 v95, v95
	v_add_f32_e32 v94, 1.0, v94
	v_add_f32_e32 v95, 1.0, v95
	v_rcp_f32_e32 v94, v94
	v_rcp_f32_e32 v95, v95
	s_nop 0
	v_pk_mul_f32 v[86:87], v[86:87], v[94:95]
	s_nop 0
	v_pk_mul_f32 v[86:87], v[86:87], v[82:83]
	v_pk_mul_f32 v[82:83], v[88:89], s[100:101]
	v_exp_f32_e32 v82, v82
	v_exp_f32_e32 v83, v83
	v_add_f32_e32 v82, 1.0, v82
	v_add_f32_e32 v83, 1.0, v83
	v_rcp_f32_e32 v82, v82
	v_rcp_f32_e32 v83, v83
	s_nop 0
; __device__ __forceinline__ float siluf_(float x) { return x * sigmoidf_(x); }
; __device__ __forceinline__ u32x4 pack8(const f32x4 a, const f32x4 b) { u32x4 w; w.x = cvt_pk_bf16(a[0], a[1]); w.y = cvt_pk_bf16(a[2], a[3]); w.z = cvt_pk_bf16(b[0], b[1]); w.w = cvt_pk_bf16(b[2], b[3]); return w; }
;     __device__ __forceinline__ void operator()(const Acc& acc, const Unit& u, int wr, int wc, int fr, int fq, const RsPre& pr) const {
;     ...
;             for (int m = 0; m < 4; ++m) { f32x4 o[2];
; #pragma unroll
;                 for (int n = 0; n < 2; ++n) { const f32x4 a1 = acc[ai][0][m][n] * rs[ai][m], a3 = acc[ai][1][m][n] * rs[ai][m];
;                     o[n] = (f32x4){siluf_(a1[0]) * a3[0], siluf_(a1[1]) * a3[1], siluf_(a1[2]) * a3[2], siluf_(a1[3]) * a3[3]}; }
;                 *(u32x4*)(ff + (size_t)(row0 + ai * 128 + m * 16) * DFF + col0) = pack8(o[0], o[1]); }
	v_pk_mul_f32 v[82:83], v[88:89], v[82:83]
	s_nop 0
	v_pk_mul_f32 v[88:89], v[82:83], v[84:85]
	v_cvt_pk_bf16_f32 v84, v86, v87
	v_cvt_pk_bf16_f32 v82, v90, v91
	v_cvt_pk_bf16_f32 v83, v92, v93
	v_cvt_pk_bf16_f32 v85, v88, v89
	v_add_u32_e32 v86, 0x2c000, v114
	global_store_dwordx4 v86, v[82:85], s[20:21]
	s_nop 1
	v_pk_mul_f32 v[82:83], v[78:79], s[100:101]
	v_exp_f32_e32 v82, v82
	v_exp_f32_e32 v83, v83
	v_add_f32_e32 v82, 1.0, v82
	v_add_f32_e32 v83, 1.0, v83
	v_rcp_f32_e32 v82, v82
	v_rcp_f32_e32 v83, v83
	s_nop 0
	v_pk_mul_f32 v[78:79], v[78:79], v[82:83]
	s_nop 0
	v_pk_mul_f32 v[74:75], v[78:79], v[74:75]
	v_pk_mul_f32 v[78:79], v[80:81], s[100:101]
	v_exp_f32_e32 v78, v78
	v_exp_f32_e32 v79, v79
	v_add_f32_e32 v78, 1.0, v78
	v_add_f32_e32 v79, 1.0, v79
	v_rcp_f32_e32 v78, v78
	v_rcp_f32_e32 v79, v79
	s_nop 0
	v_pk_mul_f32 v[78:79], v[80:81], v[78:79]
	s_nop 0
	v_pk_mul_f32 v[76:77], v[78:79], v[76:77]
	v_pk_mul_f32 v[78:79], v[70:71], s[100:101]
	v_exp_f32_e32 v78, v78
	v_exp_f32_e32 v79, v79
	v_add_f32_e32 v78, 1.0, v78
	v_add_f32_e32 v79, 1.0, v79
	v_rcp_f32_e32 v78, v78
	v_rcp_f32_e32 v79, v79
	s_nop 0
	v_pk_mul_f32 v[70:71], v[70:71], v[78:79]
	s_nop 0
	v_pk_mul_f32 v[70:71], v[70:71], v[66:67]
	v_pk_mul_f32 v[66:67], v[72:73], s[100:101]
	v_exp_f32_e32 v66, v66
	v_exp_f32_e32 v67, v67
	v_add_f32_e32 v66, 1.0, v66
	v_add_f32_e32 v67, 1.0, v67
	v_rcp_f32_e32 v66, v66
	v_rcp_f32_e32 v67, v67
	s_nop 0
	v_pk_mul_f32 v[66:67], v[72:73], v[66:67]
	s_nop 0
	v_pk_mul_f32 v[72:73], v[66:67], v[68:69]
	v_cvt_pk_bf16_f32 v68, v70, v71
	v_cvt_pk_bf16_f32 v66, v74, v75
	v_cvt_pk_bf16_f32 v67, v76, v77
	v_cvt_pk_bf16_f32 v69, v72, v73
	v_add_u32_e32 v70, 0x42000, v114
	global_store_dwordx4 v70, v[66:69], s[20:21]
	s_nop 1
	v_pk_mul_f32 v[66:67], v[62:63], s[100:101]
	v_exp_f32_e32 v66, v66
	v_exp_f32_e32 v67, v67
	v_add_f32_e32 v66, 1.0, v66
	v_add_f32_e32 v67, 1.0, v67
	v_rcp_f32_e32 v66, v66
	v_rcp_f32_e32 v67, v67
	s_nop 0
	v_pk_mul_f32 v[62:63], v[62:63], v[66:67]
	s_nop 0
	v_pk_mul_f32 v[58:59], v[62:63], v[58:59]
	v_pk_mul_f32 v[62:63], v[64:65], s[100:101]
	v_exp_f32_e32 v62, v62
	v_exp_f32_e32 v63, v63
	v_add_f32_e32 v62, 1.0, v62
	v_add_f32_e32 v63, 1.0, v63
	v_rcp_f32_e32 v62, v62
	v_rcp_f32_e32 v63, v63
	s_nop 0
	v_pk_mul_f32 v[62:63], v[64:65], v[62:63]
	s_nop 0
	v_pk_mul_f32 v[60:61], v[62:63], v[60:61]
	v_pk_mul_f32 v[62:63], v[54:55], s[100:101]
	v_exp_f32_e32 v62, v62
	v_exp_f32_e32 v63, v63
	v_add_f32_e32 v62, 1.0, v62
	v_add_f32_e32 v63, 1.0, v63
	v_rcp_f32_e32 v62, v62
	v_rcp_f32_e32 v63, v63
	s_nop 0
	v_pk_mul_f32 v[54:55], v[54:55], v[62:63]
	s_nop 0
	v_pk_mul_f32 v[54:55], v[54:55], v[50:51]
	v_pk_mul_f32 v[50:51], v[56:57], s[100:101]
	v_exp_f32_e32 v50, v50
	v_exp_f32_e32 v51, v51
	v_add_f32_e32 v50, 1.0, v50
	v_add_f32_e32 v51, 1.0, v51
	v_rcp_f32_e32 v50, v50
	v_rcp_f32_e32 v51, v51
	s_nop 0
	v_pk_mul_f32 v[50:51], v[56:57], v[50:51]
	s_nop 0
	v_pk_mul_f32 v[56:57], v[50:51], v[52:53]
	v_cvt_pk_bf16_f32 v52, v54, v55
	v_cvt_pk_bf16_f32 v50, v58, v59
	v_cvt_pk_bf16_f32 v51, v60, v61
	v_cvt_pk_bf16_f32 v53, v56, v57
	v_add_u32_e32 v54, 0xb0000, v114
	global_store_dwordx4 v54, v[50:53], s[20:21]
	s_nop 1
	v_pk_mul_f32 v[50:51], v[46:47], s[100:101]
	v_exp_f32_e32 v50, v50
	v_exp_f32_e32 v51, v51
	v_add_f32_e32 v50, 1.0, v50
	v_add_f32_e32 v51, 1.0, v51
	v_rcp_f32_e32 v50, v50
	v_rcp_f32_e32 v51, v51
	s_nop 0
	v_pk_mul_f32 v[46:47], v[46:47], v[50:51]
	s_nop 0
	v_pk_mul_f32 v[42:43], v[46:47], v[42:43]
	v_pk_mul_f32 v[46:47], v[48:49], s[100:101]
	v_exp_f32_e32 v46, v46
	v_exp_f32_e32 v47, v47
	v_add_f32_e32 v46, 1.0, v46
	v_add_f32_e32 v47, 1.0, v47
	v_rcp_f32_e32 v46, v46
	v_rcp_f32_e32 v47, v47
	s_nop 0
	v_pk_mul_f32 v[46:47], v[48:49], v[46:47]
	s_nop 0
	v_pk_mul_f32 v[44:45], v[46:47], v[44:45]
	v_pk_mul_f32 v[46:47], v[38:39], s[100:101]
	v_exp_f32_e32 v46, v46
	v_exp_f32_e32 v47, v47
	v_add_f32_e32 v46, 1.0, v46
	v_add_f32_e32 v47, 1.0, v47
	v_rcp_f32_e32 v46, v46
	v_rcp_f32_e32 v47, v47
; __device__ __forceinline__ float siluf_(float x) { return x * sigmoidf_(x); }
; __device__ __forceinline__ u32x4 pack8(const f32x4 a, const f32x4 b) { u32x4 w; w.x = cvt_pk_bf16(a[0], a[1]); w.y = cvt_pk_bf16(a[2], a[3]); w.z = cvt_pk_bf16(b[0], b[1]); w.w = cvt_pk_bf16(b[2], b[3]); return w; }
;     __device__ __forceinline__ void pre(RsPre& r, const Unit& u, int wr, int fr) const {
; #pragma unroll
;         for (int ai = 0; ai < 2; ++ai)
; #pragma unroll
;             for (int m = 0; m < 4; ++m) r.rs[ai][m] = rsv[u.pm * 256 + wr * 64 + fr + ai * 128 + m * 16]; }
;     __device__ __forceinline__ void operator()(const Acc& acc, const Unit& u, int wr, int wc, int fr, int fq, const RsPre& pr) const {
;     ...
;             for (int m = 0; m < 4; ++m) { f32x4 o[2];
; #pragma unroll
;                 for (int n = 0; n < 2; ++n) { const f32x4 a1 = acc[ai][0][m][n] * rs[ai][m], a3 = acc[ai][1][m][n] * rs[ai][m];
;                     o[n] = (f32x4){siluf_(a1[0]) * a3[0], siluf_(a1[1]) * a3[1], siluf_(a1[2]) * a3[2], siluf_(a1[3]) * a3[3]}; }
;                 *(u32x4*)(ff + (size_t)(row0 + ai * 128 + m * 16) * DFF + col0) = pack8(o[0], o[1]); }
	s_nop 0
	v_pk_mul_f32 v[38:39], v[38:39], v[46:47]
	s_nop 0
	v_pk_mul_f32 v[38:39], v[38:39], v[34:35]
	v_pk_mul_f32 v[34:35], v[40:41], s[100:101]
	v_exp_f32_e32 v34, v34
	v_exp_f32_e32 v35, v35
	v_add_f32_e32 v34, 1.0, v34
	v_add_f32_e32 v35, 1.0, v35
	v_rcp_f32_e32 v34, v34
	v_rcp_f32_e32 v35, v35
	s_nop 0
	v_pk_mul_f32 v[34:35], v[40:41], v[34:35]
	s_nop 0
	v_pk_mul_f32 v[40:41], v[34:35], v[36:37]
	v_cvt_pk_bf16_f32 v36, v38, v39
	v_cvt_pk_bf16_f32 v34, v42, v43
	v_cvt_pk_bf16_f32 v35, v44, v45
	v_cvt_pk_bf16_f32 v37, v40, v41
	v_add_u32_e32 v38, 0xc6000, v114
	global_store_dwordx4 v38, v[34:37], s[20:21]
	s_nop 1
	v_pk_mul_f32 v[34:35], v[30:31], s[100:101]
	v_exp_f32_e32 v34, v34
	v_exp_f32_e32 v35, v35
	v_add_f32_e32 v34, 1.0, v34
	v_add_f32_e32 v35, 1.0, v35
	v_rcp_f32_e32 v34, v34
	v_rcp_f32_e32 v35, v35
	s_nop 0
	v_pk_mul_f32 v[30:31], v[30:31], v[34:35]
	s_nop 0
	v_pk_mul_f32 v[26:27], v[30:31], v[26:27]
	v_pk_mul_f32 v[30:31], v[32:33], s[100:101]
	v_exp_f32_e32 v30, v30
	v_exp_f32_e32 v31, v31
	v_add_f32_e32 v30, 1.0, v30
	v_add_f32_e32 v31, 1.0, v31
	v_rcp_f32_e32 v30, v30
	v_rcp_f32_e32 v31, v31
	s_nop 0
	v_pk_mul_f32 v[30:31], v[32:33], v[30:31]
	s_nop 0
	v_pk_mul_f32 v[28:29], v[30:31], v[28:29]
	v_pk_mul_f32 v[30:31], v[22:23], s[100:101]
	v_exp_f32_e32 v30, v30
	v_exp_f32_e32 v31, v31
	v_add_f32_e32 v30, 1.0, v30
	v_add_f32_e32 v31, 1.0, v31
	v_rcp_f32_e32 v30, v30
	v_rcp_f32_e32 v31, v31
	s_nop 0
	v_pk_mul_f32 v[22:23], v[22:23], v[30:31]
	s_nop 0
	v_pk_mul_f32 v[22:23], v[22:23], v[18:19]
	v_pk_mul_f32 v[18:19], v[24:25], s[100:101]
	v_exp_f32_e32 v18, v18
	v_exp_f32_e32 v19, v19
	v_add_f32_e32 v18, 1.0, v18
	v_add_f32_e32 v19, 1.0, v19
	v_rcp_f32_e32 v18, v18
	v_rcp_f32_e32 v19, v19
	s_nop 0
	v_pk_mul_f32 v[18:19], v[24:25], v[18:19]
	s_nop 0
	v_pk_mul_f32 v[24:25], v[18:19], v[20:21]
	v_cvt_pk_bf16_f32 v20, v22, v23
	v_cvt_pk_bf16_f32 v18, v26, v27
	v_cvt_pk_bf16_f32 v19, v28, v29
	v_cvt_pk_bf16_f32 v21, v24, v25
	v_add_u32_e32 v22, 0xdc000, v114
	global_store_dwordx4 v22, v[18:21], s[20:21]
	s_nop 1
	v_pk_mul_f32 v[18:19], v[14:15], s[100:101]
	v_exp_f32_e32 v18, v18
	v_exp_f32_e32 v19, v19
	v_add_f32_e32 v18, 1.0, v18
	v_add_f32_e32 v19, 1.0, v19
	v_rcp_f32_e32 v18, v18
	v_rcp_f32_e32 v19, v19
	s_nop 0
	v_pk_mul_f32 v[14:15], v[14:15], v[18:19]
	s_nop 0
	v_pk_mul_f32 v[10:11], v[14:15], v[10:11]
	v_pk_mul_f32 v[14:15], v[16:17], s[100:101]
	v_exp_f32_e32 v14, v14
	v_exp_f32_e32 v15, v15
	v_add_f32_e32 v14, 1.0, v14
	v_add_f32_e32 v15, 1.0, v15
	v_rcp_f32_e32 v14, v14
	v_rcp_f32_e32 v15, v15
	s_nop 0
	v_pk_mul_f32 v[14:15], v[16:17], v[14:15]
	s_nop 0
	v_pk_mul_f32 v[12:13], v[14:15], v[12:13]
	v_pk_mul_f32 v[14:15], v[6:7], s[100:101]
	v_exp_f32_e32 v14, v14
	v_exp_f32_e32 v15, v15
	v_add_f32_e32 v14, 1.0, v14
	v_add_f32_e32 v15, 1.0, v15
	v_rcp_f32_e32 v14, v14
	v_rcp_f32_e32 v15, v15
	s_nop 0
	v_pk_mul_f32 v[6:7], v[6:7], v[14:15]
	s_nop 0
	v_pk_mul_f32 v[6:7], v[6:7], v[2:3]
	v_pk_mul_f32 v[2:3], v[8:9], s[100:101]
	v_exp_f32_e32 v2, v2
	v_exp_f32_e32 v3, v3
	v_add_f32_e32 v2, 1.0, v2
	v_add_f32_e32 v3, 1.0, v3
	v_rcp_f32_e32 v2, v2
	v_rcp_f32_e32 v3, v3
	s_nop 0
	v_pk_mul_f32 v[2:3], v[8:9], v[2:3]
	s_nop 0
	v_pk_mul_f32 v[8:9], v[2:3], v[4:5]
	v_cvt_pk_bf16_f32 v4, v6, v7
	v_cvt_pk_bf16_f32 v2, v10, v11
	v_cvt_pk_bf16_f32 v3, v12, v13
	v_cvt_pk_bf16_f32 v5, v8, v9
	v_add_u32_e32 v6, 0xf2000, v114
	global_store_dwordx4 v6, v[2:5], s[20:21]
	s_cbranch_vccz .LBB0_96
	s_nop 0
	v_lshl_add_u32 v2, s42, 8, v145
	v_ashrrev_i32_e32 v3, 31, v2
	v_lshl_add_u64 v[2:3], v[2:3], 2, s[4:5]
	global_load_dword v154, v[2:3], off
	global_load_dword v152, v[2:3], off offset:64
	global_load_dword v150, v[2:3], off offset:128
	global_load_dword v148, v[2:3], off offset:192
	global_load_dword v146, v[2:3], off offset:512
	global_load_dword v144, v[2:3], off offset:576
	global_load_dword v142, v[2:3], off offset:640
	global_load_dword v136, v[2:3], off offset:704
	s_mov_b64 s[60:61], 0
	s_branch .LBB0_96
